# adds next-tile LDS-DMA prefetch to the w_in tile loop and counted vmcnt waits in the context-row E-phase loop (stores stay in flight across rows)
# speedup vs baseline: 1.0021x; 1.0021x over previous
; #define STAGE(P, BASE, LD, br, kt) do { const bf16* _gb = BASE + ((long)(br) * (LD) + (long)(kt) * BK); \
;     _Pragma("unroll") for (int _i = 0; _i < 2; ++_i) { \
;       __builtin_amdgcn_global_load_lds((const unsigned*)(_gb + ((&LD == &lda) ? offA[_i] : offB[_i])), \
;         (unsigned*)((char*)(P) + tidx_ * 16 + _i * 8192), 16, 0, 0); } } while (0)
; DEV int vblock() { const int G = gridDim.x, bx = blockIdx.x; return (G % 8 == 0) ? (bx % 8) * (G / 8) + bx / 8 : bx; }
; template <class Epi, int NB>
; DEV void gemm_tile_nb(const bf16* __restrict__ A, int lda, long strideA, const bf16* __restrict__ Bt, int ldb, long strideB, int K, int brow, int bcol, Epi& epi) {
;     ...
;   for (int _i = 0; _i < 2; ++_i) { int _r, _c; stage_rc(tidx_ * 16 + _i * 8192, _r, _c); offA[_i] = (unsigned)(_r * lda + _c); offB[_i] = (unsigned)(_r * ldb + _c); }
; #pragma unroll 1
;   for (int br = 0; br < NB; ++br) {
;   STAGE(SB(0, 0), Bt, ldb, bcol, 0); STAGE(SA(0, 0), A, lda, brow, 0);
;   STAGE(SB(0, 1), Bt, ldb, bcol + HALF, 0); STAGE(SA(0, 1), A, lda, brow + HALF, 0);
; template <class Epi>
; DEV void gemm_phase(const bf16* A, int lda, const bf16* Bt, int ldb, int M, int N, int K, Epi epi) {
;   const int nM = M / 256, nN = N / 256, ntile = nM * nN;
;   for (int t = vblock(); t < ntile; t += gridDim.x) {
;     int pm, pn; tile_of(t, nM, nN, pm, pn);
;     gemm_tile(A, lda, Bt, ldb, K, pm * 256, pn * 256, epi);
.LBB0_758:
	s_andn2_b64 vcc, exec, s[0:1]
	s_cbranch_vccnz .LBB0_787
	v_readlane_b32 s0, v254, 58
	s_cmp_eq_u32 s0, 3
	s_cbranch_scc0 .LBB0_787
	v_readlane_b32 s0, v255, 3
	v_readlane_b32 s1, v255, 4
	s_add_u32 s48, s0, 0x2100000
	s_addc_u32 s49, s1, 0
	s_and_b32 s38, s11, 7
	s_cmp_eq_u32 s38, 0
	s_cselect_b64 s[38:39], -1, 0
	v_readlane_b32 s8, v254, 61
	v_readlane_b32 s9, v254, 62
	v_cndmask_b32_e64 v0, 0, 1, s[38:39]
	s_mov_b64 s[0:1], -1
	s_andn2_b64 vcc, exec, s[8:9]
	v_cmp_ne_u32_e64 s[38:39], 1, v0
	s_cbranch_vccnz .LBB0_772
	s_and_b64 vcc, exec, s[38:39]
	v_readlane_b32 s50, v250, 0
	s_mov_b32 s98, 0
	s_cbranch_vccnz .LBB0_764
	s_ashr_i32 s0, s11, 3
	v_readlane_b32 s1, v251, 38
	s_mul_i32 s0, s0, s1
	v_readlane_b32 s1, v251, 37
	s_add_i32 s50, s0, s1
	s_mov_b32 s98, 0
	s_branch .LBB0_764
.LBB0_763:
	s_add_i32 s99, s50, s11
	s_cmpk_gt_i32 s99, 0x677
	s_cbranch_scc1 .Lwin_pf_skip
	s_mul_hi_i32 s54, s99, 0xb21642c9
	s_add_i32 s54, s54, s99
	s_lshr_b32 s55, s54, 31
	s_ashr_i32 s54, s54, 7
	s_add_i32 s54, s54, s55
	s_mul_i32 s55, s54, 0xb8
	s_sub_i32 s55, s99, s55
	s_lshl_b32 s54, s54, 3
	s_and_b32 s56, s55, 7
	s_add_i32 s54, s54, s56
	s_lshr_b32 s55, s55, 3
	s_lshl_b32 s54, s54, 19
	s_lshl_b32 s55, s55, 19
	v_readlane_b32 s56, v250, 3
	v_readlane_b32 s57, v250, 4
	v_and_b32_e32 v162, 63, v179
	v_lshrrev_b32_e32 v163, 6, v179
	s_add_u32 s62, s48, s55
	s_addc_u32 s63, s49, 0
	v_lshlrev_b32_e32 v164, 4, v162
	v_and_b32_e32 v165, 32, v162
	s_add_u32 s58, s56, s54
	s_addc_u32 s59, s57, 0
	v_xor_b32_e32 v164, v164, v165
	v_lshrrev_b32_e32 v165, 1, v163
	s_add_u32 s60, s62, 0x40000
	s_addc_u32 s61, s63, 0
	v_lshrrev_b32_e32 v166, 6, v164
	v_and_b32_e32 v167, 1, v163
	s_add_u32 s56, s58, 0x40000
	s_addc_u32 s57, s59, 0
	v_lshl_add_u32 v165, v165, 4, v166
	v_and_b32_e32 v166, 62, v164
	v_lshl_or_b32 v166, v167, 6, v166
	v_readfirstlane_b32 s42, v179
	v_lshl_add_u32 v162, v165, 11, v166
	s_lshr_b32 s42, s42, 6
	s_lshl_b32 s42, s42, 10
	v_add_u32_e32 v163, 0x20000, v162
	s_add_i32 s43, s42, s74
	s_mov_b32 m0, s43
	s_add_i32 s43, s43, 0x2000
	global_load_lds_dwordx4 v162, s[62:63]
	s_mov_b32 m0, s43
	s_nop 0
	global_load_lds_dwordx4 v163, s[62:63]
	s_mov_b32 m0, s42
	s_add_i32 s43, s42, 0x2000
	global_load_lds_dwordx4 v162, s[58:59]
	s_mov_b32 m0, s43
	s_add_i32 s43, s42, s12
	global_load_lds_dwordx4 v163, s[58:59]
	s_mov_b32 m0, s43
	s_add_i32 s43, s43, 0x2000
	global_load_lds_dwordx4 v162, s[60:61]
	s_mov_b32 m0, s43
	s_add_i32 s43, s42, 0x4000
	global_load_lds_dwordx4 v163, s[60:61]
	s_mov_b32 m0, s43
	s_add_i32 s43, s42, 0x6000
	global_load_lds_dwordx4 v162, s[56:57]
	s_mov_b32 m0, s43
	s_mov_b32 s98, 1
	global_load_lds_dwordx4 v163, s[56:57]

; #define STAGE(P, BASE, LD, br, kt) do { const bf16* _gb = BASE + ((long)(br) * (LD) + (long)(kt) * BK); \
;     _Pragma("unroll") for (int _i = 0; _i < 2; ++_i) { \
;       __builtin_amdgcn_global_load_lds((const unsigned*)(_gb + ((&LD == &lda) ? offA[_i] : offB[_i])), \
;         (unsigned*)((char*)(P) + tidx_ * 16 + _i * 8192), 16, 0, 0); } } while (0)
; #define WAIT_V(n) asm volatile("s_waitcnt vmcnt(" #n ")" ::: "memory")
; #define BAR __builtin_amdgcn_s_barrier()
; template <class Epi, int NB>
; DEV void gemm_tile_nb(const bf16* __restrict__ A, int lda, long strideA, const bf16* __restrict__ Bt, int ldb, long strideB, int K, int brow, int bcol, Epi& epi) {
;     ...
;   const int wid = __builtin_amdgcn_readfirstlane(tidx_ >> 6), lane = tidx_ & 63, wr = wid >> 2, wc = wid & 3, fr = lane & 15, fq = lane >> 4;
;   f32x4 acc[2][2][4][2] = {};
;   bf16x8 At[4][2], B0[2][2], B1[2][2];
;   const int nt = K / BK;
;   const int lane_off_ = (fr * 64 + fq * 16) ^ ((fr >> 3) << 5);
;   const int aoff = wr * 8192 + lane_off_, boff = 65536 + wc * 4096 + lane_off_;
;   unsigned offA[2], offB[2];
; #pragma unroll
;   for (int _i = 0; _i < 2; ++_i) { int _r, _c; stage_rc(tidx_ * 16 + _i * 8192, _r, _c); offA[_i] = (unsigned)(_r * lda + _c); offB[_i] = (unsigned)(_r * ldb + _c); }
; #pragma unroll 1
;   for (int br = 0; br < NB; ++br) {
;   STAGE(SB(0, 0), Bt, ldb, bcol, 0); STAGE(SA(0, 0), A, lda, brow, 0);
;   STAGE(SB(0, 1), Bt, ldb, bcol + HALF, 0); STAGE(SA(0, 1), A, lda, brow + HALF, 0);
;   if (wr == 1) BAR;
;   WAIT_V(4); BAR;
;   STAGE(SB(1, 0), Bt, ldb, bcol, 1); STAGE(SA(1, 0), A, lda, brow, 1); STAGE(SB(1, 1), Bt, ldb, bcol + HALF, 1);
.LBB0_764:
	s_cmpk_gt_i32 s50, 0x677
	s_cbranch_scc1 .LBB0_771
	s_cmp_eq_u32 s98, 1
	s_cbranch_scc1 .Lwin_nowait
	s_waitcnt vmcnt(0)
.Lwin_nowait:
	v_mov_b32 v23, v179
	s_mul_hi_i32 s0, s50, 0xb21642c9
	v_ashrrev_i32_e32 v0, 31, v23
	v_lshrrev_b32_e32 v0, 26, v0
	v_add_u32_e32 v0, v23, v0
	v_ashrrev_i32_e32 v14, 6, v0
	v_bfe_i32 v0, v23, 27, 1
	v_lshlrev_b32_e32 v16, 4, v23
	v_lshrrev_b32_e32 v0, 22, v0
	v_add_u32_e32 v0, v16, v0
	v_and_b32_e32 v0, 0xfffffc00, v0
	v_sub_u32_e32 v0, v16, v0
	v_lshrrev_b32_e32 v2, 4, v0
	v_bitop3_b32 v2, v2, v0, 32 bitop3:0x6c
	v_ashrrev_i32_e32 v0, 31, v0
	v_lshrrev_b32_e32 v0, 26, v0
	v_lshlrev_b32_e32 v3, 3, v14
	v_add_u32_e32 v0, v2, v0
	s_add_i32 s0, s0, s50
	v_and_b32_e32 v3, 0x3ffff0, v3
	v_ashrrev_i32_e32 v15, 6, v0
	s_lshr_b32 s1, s0, 31
	s_ashr_i32 s0, s0, 7
	v_add_u32_e32 v0, v15, v3
	v_lshlrev_b32_e32 v3, 5, v14
	s_add_i32 s0, s0, s1
	v_and_b32_e32 v17, 32, v3
	v_mul_i32_i24_e32 v3, 64, v15
	s_mul_i32 s1, s0, 0xb8
	v_sub_u32_e32 v2, v2, v3
	s_sub_i32 s1, s50, s1
	v_ashrrev_i16_sdwa v18, v207, sext(v2) dst_sel:DWORD dst_unused:UNUSED_PAD src0_sel:DWORD src1_sel:BYTE_0
	v_add_u32_e32 v2, 0x2000, v16
	s_sext_i32_i16 s40, s1
	v_ashrrev_i32_e32 v3, 31, v2
	s_bfe_u32 s40, s40, 0x3001c
	v_lshrrev_b32_e32 v3, 22, v3
	s_add_i32 s40, s1, s40
	v_add_u32_e32 v3, v2, v3
	s_sext_i32_i16 s41, s40
	s_and_b32 s40, s40, 0xfff8
	v_ashrrev_i32_e32 v19, 10, v3
	s_sub_i32 s1, s1, s40
	v_mul_i32_i24_e32 v3, 0x400, v19
	s_sext_i32_i16 s1, s1
	v_sub_u32_e32 v2, v2, v3
	s_lshl_b32 s0, s0, 11
	s_lshl_b32 s1, s1, 8
	v_lshrrev_b32_e32 v3, 4, v2
	s_add_i32 s40, s1, s0
	s_lshl_b32 s0, s41, 5
	v_bitop3_b32 v2, v3, v2, 32 bitop3:0x6c
	s_and_b32 s0, s0, 0xffffff00
	v_ashrrev_i32_e32 v4, 31, v2
	v_readfirstlane_b32 s52, v23
	v_lshrrev_b32_e32 v4, 26, v4
	s_ashr_i32 s1, s0, 31
	s_ashr_i32 s51, s52, 8
	v_lshlrev_b32_e32 v3, 3, v19
	v_add_u32_e32 v4, v2, v4
	s_lshl_b64 s[44:45], s[0:1], 11
	v_and_b32_e32 v3, 0x3ffff0, v3
	v_ashrrev_i32_e32 v20, 6, v4
	v_lshlrev_b32_e32 v5, 5, v19
	v_and_b32_e32 v4, 0xc0, v4
	s_add_u32 s54, s48, s44
	v_lshl_or_b32 v0, v0, 10, v17
	v_add_u32_e32 v3, v20, v3
	v_and_b32_e32 v21, 32, v5
	v_sub_u32_e32 v2, v2, v4
	s_addc_u32 s55, s49, s45
	s_or_b32 s56, s0, 0x80
	s_or_b32 s58, s40, 0x80
	v_add_u32_sdwa v0, v0, sext(v18) dst_sel:DWORD dst_unused:UNUSED_PAD src0_sel:DWORD src1_sel:WORD_0
	v_ashrrev_i16_sdwa v22, v207, sext(v2) dst_sel:DWORD dst_unused:UNUSED_PAD src0_sel:DWORD src1_sel:BYTE_0
	v_lshl_or_b32 v2, v3, 10, v21
	v_add_u32_e32 v145, s74, v16
	s_ashr_i32 s41, s40, 31
	s_ashr_i32 s57, s56, 31
	s_ashr_i32 s59, s58, 31
	v_add_u32_sdwa v4, v2, sext(v22) dst_sel:DWORD dst_unused:UNUSED_PAD src0_sel:DWORD src1_sel:WORD_0
	s_lshl_b64 s[42:43], s[40:41], 11
	s_lshl_b64 s[56:57], s[56:57], 11
	s_lshl_b64 s[58:59], s[58:59], 11
	v_readlane_b32 s62, v250, 3
	v_lshlrev_b64 v[24:25], 1, v[0:1]
	v_mov_b32_e32 v5, v1
	v_add_u32_e32 v148, 0x2000, v145
	v_readlane_b32 s63, v250, 4
	s_add_u32 s60, s62, s42
	v_add_u32_e32 v146, 0, v16
	v_lshl_add_u64 v[2:3], s[54:55], 0, v[24:25]
	v_lshlrev_b64 v[26:27], 1, v[4:5]
	s_addc_u32 s61, s63, s43
	v_lshl_add_u64 v[6:7], s[54:55], 0, v[26:27]
	v_add_u32_e32 v150, 0x2000, v146
	s_add_u32 s56, s48, s56
	v_add_u32_e32 v147, s12, v16
	v_lshl_add_u64 v[12:13], s[60:61], 0, v[24:25]
	s_addc_u32 s57, s49, s57
	v_lshl_add_u64 v[8:9], s[60:61], 0, v[26:27]
	v_add_u32_e32 v151, 0x2000, v147
	s_add_u32 s58, s62, s58
	v_add_u32_e32 v149, 0x4000, v146
	v_lshl_add_u64 v[10:11], s[56:57], 0, v[24:25]
	s_addc_u32 s59, s63, s59
	v_lshl_add_u64 v[4:5], s[56:57], 0, v[26:27]
	v_add_u32_e32 v152, 0x6000, v146
	v_lshl_add_u64 v[132:133], s[58:59], 0, v[24:25]
	v_lshl_add_u64 v[130:131], s[58:59], 0, v[26:27]
	s_cmp_eq_u32 s98, 1
	s_cbranch_scc1 .Lwin_ld_skip
	v_readfirstlane_b32 s1, v145
	s_mov_b32 m0, s1
	v_readfirstlane_b32 s1, v148
	global_load_lds_dwordx4 v[2:3], off
	s_mov_b32 m0, s1
	v_readfirstlane_b32 s1, v146
	global_load_lds_dwordx4 v[6:7], off
	s_mov_b32 m0, s1
	v_readfirstlane_b32 s1, v150
	global_load_lds_dwordx4 v[12:13], off
	s_mov_b32 m0, s1
	v_readfirstlane_b32 s1, v147
	global_load_lds_dwordx4 v[8:9], off
	s_mov_b32 m0, s1
	v_readfirstlane_b32 s1, v151
	global_load_lds_dwordx4 v[10:11], off
	s_mov_b32 m0, s1
	v_readfirstlane_b32 s1, v149
	global_load_lds_dwordx4 v[4:5], off
	s_mov_b32 m0, s1
	v_readfirstlane_b32 s1, v152
	global_load_lds_dwordx4 v[132:133], off
	s_mov_b32 m0, s1
	s_nop 0
	global_load_lds_dwordx4 v[130:131], off
.Lwin_ld_skip:
	s_cmp_lg_u32 s51, 1
	s_cbranch_scc1 .LBB0_767
	s_barrier
.LBB0_767:
	v_and_b32_e32 v143, 15, v23
	s_bfe_u32 s1, s52, 0x20006
	v_bfe_u32 v142, v23, 4, 2
	v_lshlrev_b32_e32 v0, 6, v143
	v_lshlrev_b32_e32 v23, 2, v23
	v_lshl_or_b32 v0, v142, 4, v0
	v_and_b32_e32 v23, 32, v23
	s_lshl_b32 s41, s51, 13
	s_lshl_b32 s53, s1, 12
	v_add_u32_e32 v153, s13, v16
	v_bitop3_b32 v24, v0, s53, v23 bitop3:0xde
	v_bitop3_b32 v23, v0, s41, v23 bitop3:0xde
	s_mov_b64 s[54:55], 0x80
	v_readfirstlane_b32 s41, v153
	v_add_u32_e32 v154, 0x2000, v153
	v_lshl_add_u64 v[2:3], v[2:3], 0, s[54:55]
	s_mov_b32 m0, s41
	v_readfirstlane_b32 s41, v154
	v_add_u32_e32 v155, 0x8000, v146
	s_cmp_eq_u32 s98, 0
	s_cbranch_scc1 .Lwin_w4a
	s_waitcnt vmcnt(20)
	s_branch .Lwin_w4b

; #define STAGE(P, BASE, LD, br, kt) do { const bf16* _gb = BASE + ((long)(br) * (LD) + (long)(kt) * BK); \
;     _Pragma("unroll") for (int _i = 0; _i < 2; ++_i) { \
;       __builtin_amdgcn_global_load_lds((const unsigned*)(_gb + ((&LD == &lda) ? offA[_i] : offB[_i])), \
;         (unsigned*)((char*)(P) + tidx_ * 16 + _i * 8192), 16, 0, 0); } } while (0)
; #define WAIT_V(n) asm volatile("s_waitcnt vmcnt(" #n ")" ::: "memory")
; #define BAR __builtin_amdgcn_s_barrier()
; template <class Epi, int NB>
; DEV void gemm_tile_nb(const bf16* __restrict__ A, int lda, long strideA, const bf16* __restrict__ Bt, int ldb, long strideB, int K, int brow, int bcol, Epi& epi) {
;     ...
;   WAIT_V(4); BAR;
;   STAGE(SB(1, 0), Bt, ldb, bcol, 1); STAGE(SA(1, 0), A, lda, brow, 1); STAGE(SB(1, 1), Bt, ldb, bcol + HALF, 1);
;   WAIT_V(6); BAR;
.Lwin_w4b:
	s_barrier
	global_load_lds_dwordx4 v[2:3], off
	v_lshl_add_u64 v[2:3], v[6:7], 0, s[54:55]
	s_mov_b32 m0, s41
	v_readfirstlane_b32 s41, v155
	v_add_u32_e32 v156, 0xa000, v146
	global_load_lds_dwordx4 v[2:3], off
	v_lshl_add_u64 v[2:3], v[12:13], 0, s[54:55]
	s_mov_b32 m0, s41
	v_readfirstlane_b32 s41, v156
	v_add_u32_e32 v157, s14, v16
	global_load_lds_dwordx4 v[2:3], off
	v_lshl_add_u64 v[2:3], v[8:9], 0, s[54:55]
	s_mov_b32 m0, s41
	v_readfirstlane_b32 s41, v157
	v_add_u32_e32 v158, 0x2000, v157
	global_load_lds_dwordx4 v[2:3], off
	v_lshl_add_u64 v[2:3], v[10:11], 0, s[54:55]
	s_mov_b32 m0, s41
	v_readfirstlane_b32 s41, v158
	global_load_lds_dwordx4 v[2:3], off
	v_lshl_add_u64 v[2:3], v[4:5], 0, s[54:55]
	s_mov_b32 m0, s41
	v_lshlrev_b32_e32 v0, 13, v14
	global_load_lds_dwordx4 v[2:3], off
	v_and_b32_e32 v0, 0xffffc000, v0
	v_lshl_add_u32 v0, v15, 10, v0
	v_or_b32_e32 v0, v0, v17
	v_add_u32_sdwa v0, v0, sext(v18) dst_sel:DWORD dst_unused:UNUSED_PAD src0_sel:DWORD src1_sel:WORD_0
	v_lshlrev_b64 v[2:3], 1, v[0:1]
	v_lshlrev_b32_e32 v0, 13, v19
	v_and_b32_e32 v0, 0xffffc000, v0
	v_readlane_b32 s8, v254, 63
	v_lshl_add_u32 v0, v20, 10, v0
	s_add_u32 s44, s8, s44
	v_or_b32_e32 v0, v0, v21
	s_addc_u32 s45, 0, s45
	s_cmp_eq_u32 s98, 0
	s_cbranch_scc1 .Lwin_w6a
	s_waitcnt vmcnt(22)
	s_branch .Lwin_w6b

; #define STAGE(P, BASE, LD, br, kt) do { const bf16* _gb = BASE + ((long)(br) * (LD) + (long)(kt) * BK); \
;     _Pragma("unroll") for (int _i = 0; _i < 2; ++_i) { \
;       __builtin_amdgcn_global_load_lds((const unsigned*)(_gb + ((&LD == &lda) ? offA[_i] : offB[_i])), \
;         (unsigned*)((char*)(P) + tidx_ * 16 + _i * 8192), 16, 0, 0); } } while (0)
; #define WAIT_V(n) asm volatile("s_waitcnt vmcnt(" #n ")" ::: "memory")
; #define BAR __builtin_amdgcn_s_barrier()
; template <class Epi, int NB>
; DEV void gemm_tile_nb(const bf16* __restrict__ A, int lda, long strideA, const bf16* __restrict__ Bt, int ldb, long strideB, int K, int brow, int bcol, Epi& epi) {
;     ...
;   f32x4 acc[2][2][4][2] = {};
;   bf16x8 At[4][2], B0[2][2], B1[2][2];
;   const int nt = K / BK;
;   const int lane_off_ = (fr * 64 + fq * 16) ^ ((fr >> 3) << 5);
;   const int aoff = wr * 8192 + lane_off_, boff = 65536 + wc * 4096 + lane_off_;
;   unsigned offA[2], offB[2];
; #pragma unroll
;   for (int _i = 0; _i < 2; ++_i) { int _r, _c; stage_rc(tidx_ * 16 + _i * 8192, _r, _c); offA[_i] = (unsigned)(_r * lda + _c); offB[_i] = (unsigned)(_r * ldb + _c); }
; #pragma unroll 1
;   for (int br = 0; br < NB; ++br) {
;   STAGE(SB(0, 0), Bt, ldb, bcol, 0); STAGE(SA(0, 0), A, lda, brow, 0);
;   STAGE(SB(0, 1), Bt, ldb, bcol + HALF, 0); STAGE(SA(0, 1), A, lda, brow + HALF, 0);
;   if (wr == 1) BAR;
;   WAIT_V(4); BAR;
;   STAGE(SB(1, 0), Bt, ldb, bcol, 1); STAGE(SA(1, 0), A, lda, brow, 1); STAGE(SB(1, 1), Bt, ldb, bcol + HALF, 1);
;   WAIT_V(6); BAR;
;   for (int t = 0; t < nt - 2; t += 2) {
.Lwin_w6b:
	v_add_u32_sdwa v0, v0, sext(v22) dst_sel:DWORD dst_unused:UNUSED_PAD src0_sel:DWORD src1_sel:WORD_0
	v_or_b32_e32 v24, 0x10000, v24
	v_lshl_add_u64 v[134:135], s[44:45], 0, v[2:3]
	v_lshlrev_b64 v[4:5], 1, v[0:1]
	v_lshl_add_u64 v[138:139], s[42:43], 0, v[2:3]
	v_mov_b32_e32 v2, 0
	v_lshl_add_u64 v[136:137], s[44:45], 0, v[4:5]
	v_lshl_add_u64 v[140:141], s[42:43], 0, v[4:5]
	s_mov_b32 s41, -2
	v_add_u32_e32 v144, 0, v24
	v_add_u32_e32 v0, 0, v23
	v_mov_b32_e32 v3, v2
	v_mov_b32_e32 v4, v2
	v_mov_b32_e32 v5, v2
	v_mov_b32_e32 v6, v2
	v_mov_b32_e32 v7, v2
	v_mov_b32_e32 v8, v2
	v_mov_b32_e32 v9, v2
	v_mov_b32_e32 v10, v2
	v_mov_b32_e32 v11, v2
	v_mov_b32_e32 v12, v2
	v_mov_b32_e32 v13, v2
	v_mov_b32_e32 v14, v2
	v_mov_b32_e32 v15, v2
	v_mov_b32_e32 v16, v2
	v_mov_b32_e32 v17, v2
	v_mov_b32_e32 v18, v2
	v_mov_b32_e32 v19, v2
	v_mov_b32_e32 v20, v2
	v_mov_b32_e32 v21, v2
	v_mov_b32_e32 v22, v2
	v_mov_b32_e32 v23, v2
	v_mov_b32_e32 v24, v2
	v_mov_b32_e32 v25, v2
	v_mov_b32_e32 v26, v2
	v_mov_b32_e32 v27, v2
	s_waitcnt vmcnt(0)
	v_mov_b32_e32 v28, v2
	v_mov_b32_e32 v29, v2
	v_mov_b32_e32 v30, v2
	v_mov_b32_e32 v31, v2
	v_mov_b32_e32 v32, v2
	v_mov_b32_e32 v33, v2
	v_mov_b32_e32 v34, v2
	v_mov_b32_e32 v35, v2
	v_mov_b32_e32 v36, v2
	v_mov_b32_e32 v37, v2
	v_mov_b32_e32 v38, v2
	v_mov_b32_e32 v39, v2
	v_mov_b32_e32 v40, v2
	v_mov_b32_e32 v41, v2
	v_mov_b32_e32 v42, v2
	v_mov_b32_e32 v43, v2
	v_mov_b32_e32 v44, v2
	v_mov_b32_e32 v45, v2
	v_mov_b32_e32 v46, v2
	v_mov_b32_e32 v47, v2
	v_mov_b32_e32 v48, v2
	v_mov_b32_e32 v49, v2
	v_mov_b32_e32 v50, v2
	v_mov_b32_e32 v51, v2
	v_mov_b32_e32 v52, v2
	v_mov_b32_e32 v53, v2
	v_mov_b32_e32 v54, v2
	v_mov_b32_e32 v55, v2
	v_mov_b32_e32 v56, v2
	v_mov_b32_e32 v57, v2
	v_mov_b32_e32 v58, v2
	v_mov_b32_e32 v59, v2
	v_mov_b32_e32 v60, v2
	v_mov_b32_e32 v61, v2
	v_mov_b32_e32 v62, v2
	v_mov_b32_e32 v63, v2
	v_mov_b32_e32 v64, v2
	v_mov_b32_e32 v65, v2
	v_mov_b32_e32 v70, v2
	v_mov_b32_e32 v71, v2
	v_mov_b32_e32 v72, v2
	v_mov_b32_e32 v73, v2
	v_mov_b32_e32 v86, v2
	v_mov_b32_e32 v87, v2
	v_mov_b32_e32 v88, v2
	v_mov_b32_e32 v89, v2
	v_mov_b32_e32 v90, v2
	v_mov_b32_e32 v91, v2
	v_mov_b32_e32 v92, v2
	v_mov_b32_e32 v93, v2
	v_mov_b32_e32 v94, v2
	v_mov_b32_e32 v95, v2
	v_mov_b32_e32 v96, v2
	v_mov_b32_e32 v97, v2
	v_mov_b32_e32 v98, v2
	v_mov_b32_e32 v99, v2
	v_mov_b32_e32 v100, v2
	v_mov_b32_e32 v101, v2
	v_mov_b32_e32 v102, v2
	v_mov_b32_e32 v103, v2
	v_mov_b32_e32 v104, v2
	v_mov_b32_e32 v105, v2
	v_mov_b32_e32 v106, v2
	v_mov_b32_e32 v107, v2
	v_mov_b32_e32 v108, v2
	v_mov_b32_e32 v109, v2
	v_mov_b32_e32 v110, v2
	v_mov_b32_e32 v111, v2
	v_mov_b32_e32 v112, v2
	v_mov_b32_e32 v113, v2
	v_mov_b32_e32 v114, v2
	v_mov_b32_e32 v115, v2
	v_mov_b32_e32 v116, v2
	v_mov_b32_e32 v117, v2
	v_mov_b32_e32 v118, v2
	v_mov_b32_e32 v119, v2
	v_mov_b32_e32 v120, v2
	v_mov_b32_e32 v121, v2
	v_mov_b32_e32 v122, v2
	v_mov_b32_e32 v123, v2
	v_mov_b32_e32 v124, v2
	v_mov_b32_e32 v125, v2
	v_mov_b32_e32 v126, v2
	v_mov_b32_e32 v127, v2
	v_mov_b32_e32 v128, v2
	v_mov_b32_e32 v129, v2
	v_mov_b32_e32 v66, v2
	v_mov_b32_e32 v67, v2
	v_mov_b32_e32 v68, v2
	v_mov_b32_e32 v69, v2
	v_mov_b32_e32 v74, v2
	v_mov_b32_e32 v75, v2
	v_mov_b32_e32 v76, v2
	v_mov_b32_e32 v77, v2
	v_mov_b32_e32 v78, v2
	v_mov_b32_e32 v79, v2
	v_mov_b32_e32 v80, v2
	v_mov_b32_e32 v81, v2
	v_mov_b32_e32 v82, v2
	v_mov_b32_e32 v83, v2
	v_mov_b32_e32 v84, v2
	v_mov_b32_e32 v85, v2
	s_mov_b64 s[44:45], 0xabe4080
	s_mov_b64 s[54:55], 0x2100100
	s_mov_b64 s[56:57], 0x2140100
	s_mov_b64 s[58:59], 0xabe4100
	s_mov_b64 s[60:61], 0x2100180
	s_mov_b64 s[62:63], 0x2140180
	s_barrier

; DEV float bf2f(unsigned short h) { return __uint_as_float(((unsigned)h) << 16); }
; DEV void e_phase(const Params& p, int l, int mode, int t_begin, int t_end, int widx, int wcount, bool ctxsum) {
;     ...
;   while (t < t_end) {
;     const int mi = t < TL ? (t >> 11) : 8;
;     if (mi != cur_mi) {
;       cur_mi = mi;
;       const float* gate = MOD + (size_t)l * 9 * 9216 + (size_t)mi * 9216 + (3 * sp + 2) * 1024;
;       const float* gp = npost + (l * 3 + sp) * 1024;
;       const float* gpre = npre + (ln * 3 + s) * 1024;
;       const float* mrow = MOD + (size_t)ln * 9 * 9216 + (size_t)mi * 9216;
; #pragma unroll
;       for (int i = 0; i < 4; ++i) { const int c0 = i * 256 + lane * 4;
;         if (mode != 0) { gt[i] = *reinterpret_cast<const f32x4*>(gate + c0); gg[i] = *reinterpret_cast<const f32x4*>(gp + c0); }
;         if (!final_out) { g2[i] = *reinterpret_cast<const f32x4*>(gpre + c0);
;           sh[i] = *reinterpret_cast<const f32x4*>(mrow + (3 * s) * 1024 + c0);
;           sc[i] = *reinterpret_cast<const f32x4*>(mrow + (3 * s + 1) * 1024 + c0); } }
;     }
;     f32x4 xv[4], yv[4];
; #pragma unroll
;     for (int i = 0; i < 4; ++i) { xv[i] = xn[i];
;       if (mode != 0) yv[i] = ctxsum ? (ya[i] + yb[i]) : (f32x4){bf2f(yh[i][0]), bf2f(yh[i][1]), bf2f(yh[i][2]), bf2f(yh[i][3])}; }
;     const int tn = t + 1;
;     if (tn < t_end) LOADROW(tn);
.LBB0_885:
	s_mov_b64 s[0:1], 0x800
	v_lshl_add_u64 v[198:199], v[198:199], 0, s[0:1]
	s_mov_b64 s[0:1], 0x1000
	s_waitcnt vmcnt(12)
	v_mov_b64_e32 v[66:67], v[158:159]
	v_mov_b64_e32 v[78:79], v[154:155]
	v_mov_b64_e32 v[90:91], v[134:135]
	v_mov_b64_e32 v[94:95], v[130:131]
	s_waitcnt vmcnt(10)
	v_mov_b64_e32 v[122:123], v[166:167]
	v_mov_b64_e32 v[114:115], v[162:163]
	v_mov_b64_e32 v[106:107], v[142:143]
	v_mov_b64_e32 v[98:99], v[138:139]
	s_waitcnt vmcnt(8)
	v_mov_b64_e32 v[126:127], v[174:175]
	v_mov_b64_e32 v[118:119], v[170:171]
	v_mov_b64_e32 v[110:111], v[150:151]
	v_mov_b64_e32 v[102:103], v[146:147]
	v_lshl_add_u64 v[200:201], v[200:201], 0, s[0:1]
	s_and_b64 vcc, exec, s[44:45]
	v_mov_b64_e32 v[68:69], v[160:161]
	v_mov_b64_e32 v[80:81], v[156:157]
	v_mov_b64_e32 v[92:93], v[136:137]
	v_mov_b64_e32 v[96:97], v[132:133]
	v_mov_b64_e32 v[124:125], v[168:169]
	v_mov_b64_e32 v[116:117], v[164:165]
	v_mov_b64_e32 v[108:109], v[144:145]
	v_mov_b64_e32 v[100:101], v[140:141]
	v_mov_b64_e32 v[128:129], v[176:177]
	v_mov_b64_e32 v[120:121], v[172:173]
	v_mov_b64_e32 v[112:113], v[152:153]
	v_mov_b64_e32 v[104:105], v[148:149]
	s_mov_b32 s42, s49
	s_cbranch_vccnz .LBB0_909

; DEV float bf2f(unsigned short h) { return __uint_as_float(((unsigned)h) << 16); }
; DEV void e_phase(const Params& p, int l, int mode, int t_begin, int t_end, int widx, int wcount, bool ctxsum) {
;     ...
;   const int rpw = (t_end - t_begin + wcount - 1) / wcount;
;   int t = t_begin + widx * rpw;
;   t_end = min(t_end, t + rpw);
;   if (t < t_end) LOADROW(t);
;   int cur_mi = -1;
;   f32x4 gt[4], gg[4], g2[4], sh[4], sc[4];
;   while (t < t_end) {
;     const int mi = t < TL ? (t >> 11) : 8;
;     if (mi != cur_mi) {
;       cur_mi = mi;
;       const float* gate = MOD + (size_t)l * 9 * 9216 + (size_t)mi * 9216 + (3 * sp + 2) * 1024;
;       const float* gp = npost + (l * 3 + sp) * 1024;
;       const float* gpre = npre + (ln * 3 + s) * 1024;
;       const float* mrow = MOD + (size_t)ln * 9 * 9216 + (size_t)mi * 9216;
; #pragma unroll
;       for (int i = 0; i < 4; ++i) { const int c0 = i * 256 + lane * 4;
;         if (mode != 0) { gt[i] = *reinterpret_cast<const f32x4*>(gate + c0); gg[i] = *reinterpret_cast<const f32x4*>(gp + c0); }
;         if (!final_out) { g2[i] = *reinterpret_cast<const f32x4*>(gpre + c0);
;           sh[i] = *reinterpret_cast<const f32x4*>(mrow + (3 * s) * 1024 + c0);
;           sc[i] = *reinterpret_cast<const f32x4*>(mrow + (3 * s + 1) * 1024 + c0); } }
;     }
;     f32x4 xv[4], yv[4];
; #pragma unroll
;     for (int i = 0; i < 4; ++i) { xv[i] = xn[i];
;       if (mode != 0) yv[i] = ctxsum ? (ya[i] + yb[i]) : (f32x4){bf2f(yh[i][0]), bf2f(yh[i][1]), bf2f(yh[i][2]), bf2f(yh[i][3])}; }
;     const int tn = t + 1;
;     if (tn < t_end) LOADROW(tn);
.LBB0_895:
	s_waitcnt vmcnt(0)
	s_mov_b32 s48, s57
.LBB0_896:
	s_add_i32 s49, s42, 1
	s_cmp_ge_i32 s49, s53
	s_cselect_b64 s[44:45], -1, 0
	s_nop 0
	v_mov_b64_e32 v[160:161], v[68:69]
	v_mov_b64_e32 v[156:157], v[80:81]
	v_mov_b64_e32 v[136:137], v[92:93]
	v_mov_b64_e32 v[132:133], v[96:97]
	s_nop 0
	v_mov_b64_e32 v[168:169], v[124:125]
	v_mov_b64_e32 v[164:165], v[116:117]
	v_mov_b64_e32 v[144:145], v[108:109]
	v_mov_b64_e32 v[140:141], v[100:101]
	s_nop 0
	v_mov_b64_e32 v[176:177], v[128:129]
	v_mov_b64_e32 v[172:173], v[120:121]
	v_mov_b64_e32 v[152:153], v[112:113]
	v_mov_b64_e32 v[148:149], v[104:105]
	s_and_b64 vcc, exec, s[44:45]
	v_lshl_add_u64 v[202:203], s[88:89], 0, v[200:201]
	v_mov_b64_e32 v[158:159], v[66:67]
	v_mov_b64_e32 v[154:155], v[78:79]
	v_mov_b64_e32 v[134:135], v[90:91]
	v_mov_b64_e32 v[130:131], v[94:95]
	v_mov_b64_e32 v[166:167], v[122:123]
	v_mov_b64_e32 v[162:163], v[114:115]
	v_mov_b64_e32 v[142:143], v[106:107]
	v_mov_b64_e32 v[138:139], v[98:99]
	v_mov_b64_e32 v[174:175], v[126:127]
	v_mov_b64_e32 v[170:171], v[118:119]
	v_mov_b64_e32 v[150:151], v[110:111]
	v_mov_b64_e32 v[146:147], v[102:103]
	s_cbranch_vccnz .LBB0_898
	s_add_i32 s50, s42, 0xffffc001
	s_ashr_i32 s51, s50, 31
	s_lshl_b64 s[50:51], s[50:51], 12
	v_add_co_u32_e32 v158, vcc, 0x63a5000, v202
	v_lshl_add_u64 v[166:167], v[196:197], 0, s[50:51]
	s_nop 0
	v_addc_co_u32_e32 v159, vcc, 0, v203, vcc
	v_add_co_u32_e32 v174, vcc, 0x800000, v166
	s_nop 1
	v_addc_co_u32_e32 v175, vcc, 0, v167, vcc
	global_load_dwordx4 v[130:133], v[158:159], off nt
	global_load_dwordx4 v[134:137], v[158:159], off offset:1024 nt
	global_load_dwordx4 v[138:141], v[166:167], off
	global_load_dwordx4 v[142:145], v[166:167], off offset:1024
	global_load_dwordx4 v[146:149], v[174:175], off
	global_load_dwordx4 v[150:153], v[174:175], off offset:1024
	global_load_dwordx4 v[154:157], v[158:159], off offset:2048 nt
	s_nop 0
	global_load_dwordx4 v[158:161], v[158:159], off offset:3072 nt
	s_nop 0
	global_load_dwordx4 v[162:165], v[166:167], off offset:2048
	s_nop 0
	global_load_dwordx4 v[166:169], v[166:167], off offset:3072
	s_nop 0
	global_load_dwordx4 v[170:173], v[174:175], off offset:2048
	s_nop 0
	global_load_dwordx4 v[174:177], v[174:175], off offset:3072

; DEV void e_phase(const Params& p, int l, int mode, int t_begin, int t_end, int widx, int wcount, bool ctxsum) {
;     ...
; #pragma unroll
;       for (int i = 0; i < 4; ++i) { const int c0 = i * 256 + lane * 4;
; #pragma unroll
;         for (int e = 0; e < 4; ++e) xv[i][e] += wgt * gt[i][e] * (yv[i][e] * rstd * gg[i][e]);
;         if (!final_out) __builtin_nontemporal_store(xv[i], reinterpret_cast<f32x4*>(X + (size_t)t * 1024 + c0)); }
;     }
;     if (final_out) {
;       if (t < TL) {
; #pragma unroll
;         for (int i = 0; i < 4; ++i) *reinterpret_cast<f32x4*>(p.out + (size_t)t * 1024 + i * 256 + lane * 4) = xv[i];
;       }
.LBB0_906:
	s_andn2_b64 vcc, exec, s[0:1]
	s_cbranch_vccnz .LBB0_885
	s_waitcnt vmcnt(0)
	s_cmpk_gt_i32 s42, 0x3fff
	s_cbranch_scc1 .LBB0_885
	v_readlane_b32 s56, v253, 55
	v_readlane_b32 s70, v254, 5
	v_readlane_b32 s71, v254, 6
	v_readlane_b32 s57, v253, 56
	v_readlane_b32 s58, v253, 57
	v_lshl_add_u64 v[98:99], s[70:71], 0, v[200:201]
	v_readlane_b32 s59, v253, 58
	v_readlane_b32 s60, v253, 59
	v_readlane_b32 s61, v253, 60
	v_readlane_b32 s62, v253, 61
	v_readlane_b32 s63, v253, 62
	v_readlane_b32 s64, v253, 63
	v_readlane_b32 s65, v254, 0
	v_readlane_b32 s66, v254, 1
	v_readlane_b32 s67, v254, 2
	v_readlane_b32 s68, v254, 3
	v_readlane_b32 s69, v254, 4
	global_store_dwordx4 v[98:99], v[94:97], off
	global_store_dwordx4 v[98:99], v[90:93], off offset:1024
	global_store_dwordx4 v[98:99], v[78:81], off offset:2048
	global_store_dwordx4 v[98:99], v[66:69], off offset:3072
	s_branch .LBB0_885
